# GROWS: L2 prefetch of A tile 4 K-steps ahead (1 global_load_dword per wave per iteration), vmcnt recounted
# baseline (speedup 1.0000x reference)
; template <class Epi, class Sched, bool ALIGN_EPI = false, bool SP2 = false>
; __device__ __forceinline__ void gemm_phase(PG8_LAS unsigned char* lds, const Gemm g, const Sched& S, const Epi& E, const int tid) {
;     const int wid = __builtin_amdgcn_readfirstlane(tid >> 6), lane = tid & 63, wr = wid >> 2, wc = wid & 3, fr = lane & 15, fq = lane >> 4;
;     const int K = g.K, nt = (g.Kloop ? g.Kloop : g.K) / BK;
;     unsigned voffA[2], voffB[2];
; #pragma unroll
;     for (int i = 0; i < 2; ++i) { int R, C; stage_rc(tid * 16 + i * 8192, R, C); const int Rb = Epi::PERM ? ((R & ~31) + perm32(R & 31)) : R;
;         voffA[i] = (unsigned)(R * K + C) * 2u; voffB[i] = (unsigned)(Rb * K + C) * 2u; }
;     const size_t kstep = (size_t)(BK * 2);
;     const size_t hstep = (size_t)HALF * K * 2;
;     const size_t tstep = 2 * hstep;
;     const unsigned ldsw = (unsigned)wid * 1024u;
;     const int aoff = lds_byte(wr * 64 + fr, fq * 8), boff = lds_byte(wc * 32 + fr, fq * 8);
.LBB0_449:
	v_bfe_i32 v3, v164, 27, 1
	v_lshlrev_b32_e32 v1, 4, v164
	v_lshrrev_b32_e32 v3, 22, v3
	v_add_u32_e32 v3, v1, v3
	v_and_b32_e32 v3, 0xfffffc00, v3
	v_sub_u32_e32 v3, v1, v3
	v_lshrrev_b32_e32 v4, 4, v3
	v_ashrrev_i32_e32 v0, 31, v164
	v_bitop3_b32 v3, v4, v3, 32 bitop3:0x6c
	v_lshrrev_b32_e32 v0, 26, v0
	s_waitcnt lgkmcnt(0)
	v_ashrrev_i32_e32 v5, 31, v3
	v_add_u32_e32 v0, v164, v0
	v_lshrrev_b32_e32 v5, 26, v5
	v_ashrrev_i32_e32 v0, 6, v0
	v_add_u32_e32 v5, v3, v5
	v_lshlrev_b32_e32 v4, 3, v0
	v_ashrrev_i32_e32 v6, 6, v5
	v_and_b32_e32 v5, 0xc0, v5
	v_and_b32_e32 v4, -16, v4
	v_lshlrev_b32_e32 v0, 5, v0
	v_sub_u32_e32 v3, v3, v5
	v_add_u32_e32 v4, v6, v4
	v_and_b32_e32 v0, 32, v0
	v_ashrrev_i16_sdwa v3, v231, sext(v3) dst_sel:DWORD dst_unused:UNUSED_PAD src0_sel:DWORD src1_sel:BYTE_0
	v_add_u32_sdwa v3, v0, sext(v3) dst_sel:DWORD dst_unused:UNUSED_PAD src0_sel:DWORD src1_sel:WORD_0
	v_lshlrev_b32_e32 v0, 1, v4
	v_lshrrev_b32_e32 v5, 2, v4
	v_and_b32_e32 v6, 3, v6
	s_mov_b32 s2, 0x7fffffe0
	v_and_b32_e32 v0, 24, v0
	v_and_b32_e32 v5, 4, v5
	v_and_or_b32 v6, v4, s2, v6
	v_or3_b32 v5, v6, v5, v0
	v_readlane_b32 s6, v254, 15
	v_add_u32_e32 v1, 0x2000, v1
	s_add_u32 s10, s90, 0x16608000
	v_mul_lo_u32 v0, s6, v4
	v_mul_lo_u32 v4, s6, v5
	v_lshrrev_b32_e32 v255, 1, v164
	v_mul_lo_u32 v255, s6, v255
	v_and_b32_e32 v250, 1, v164
	v_lshlrev_b32_e32 v250, 6, v250
	v_add_lshl_u32 v255, v255, v250, 1
	v_add_lshl_u32 v0, v0, v3, 1
	v_add_lshl_u32 v146, v4, v3, 1
	v_ashrrev_i32_e32 v3, 31, v1
	v_lshrrev_b32_e32 v3, 22, v3
	v_add_u32_e32 v3, v1, v3
	v_ashrrev_i32_e32 v3, 10, v3
	v_mul_i32_i24_e32 v4, 0x400, v3
	v_sub_u32_e32 v1, v1, v4
	v_lshrrev_b32_e32 v4, 4, v1
	v_bitop3_b32 v1, v4, v1, 32 bitop3:0x6c
	v_ashrrev_i32_e32 v5, 31, v1
	v_lshrrev_b32_e32 v5, 26, v5
	s_addc_u32 s11, s91, 0
	v_lshlrev_b32_e32 v4, 3, v3
	v_add_u32_e32 v5, v1, v5
	s_add_u32 s12, s90, 0xa14000
	v_and_b32_e32 v4, -16, v4
	v_ashrrev_i32_e32 v6, 6, v5
	s_addc_u32 s13, s91, 0
	v_add_u32_e32 v4, v6, v4
	v_and_b32_e32 v6, 3, v6
	s_lshl_b32 s14, s6, 8
	s_mov_b32 s15, s35
	v_and_or_b32 v6, v4, s2, v6
	s_lshl_b64 s[16:17], s[14:15], 1
	s_lshl_b32 s2, s6, 16
	v_readlane_b32 s4, v254, 18
	v_readlane_b32 s5, v254, 19
	s_add_u32 s2, s4, s2
	v_and_b32_e32 v5, 0xc0, v5
	s_addc_u32 s3, s5, 0
	v_readlane_b32 s4, v253, 29
	v_lshlrev_b32_e32 v3, 5, v3
	v_sub_u32_e32 v1, v1, v5
	v_readlane_b32 s5, v253, 30
	s_add_u32 s18, s2, s4
	v_and_b32_e32 v3, 32, v3
	v_ashrrev_i16_sdwa v1, v231, sext(v1) dst_sel:DWORD dst_unused:UNUSED_PAD src0_sel:DWORD src1_sel:BYTE_0
	s_addc_u32 s19, s3, s5
	v_readlane_b32 s2, v254, 20
	v_add_u32_sdwa v1, v3, sext(v1) dst_sel:DWORD dst_unused:UNUSED_PAD src0_sel:DWORD src1_sel:WORD_0
	v_lshlrev_b32_e32 v3, 1, v4
	v_lshrrev_b32_e32 v5, 2, v4
	v_readlane_b32 s3, v254, 21
	s_add_u32 s20, s2, s4
	v_and_b32_e32 v3, 24, v3
	v_and_b32_e32 v5, 4, v5
	s_addc_u32 s21, s3, s5
	s_lshr_b32 s60, s6, 4
	v_readlane_b32 s2, v251, 34
	v_or3_b32 v3, v6, v5, v3
	v_readlane_b32 s3, v251, 35
	s_add_u32 s2, s90, s2
	v_mul_lo_u32 v4, s6, v4
	v_mul_lo_u32 v3, s6, v3
	s_addc_u32 s3, s91, s3
	v_add_lshl_u32 v166, v4, v1, 1
	v_add_lshl_u32 v168, v3, v1, 1
	v_and_b32_e32 v3, 15, v164
	v_bfe_u32 v4, v164, 4, 2
	v_lshlrev_b32_e32 v5, 2, v164
	s_add_u32 s22, s2, 0x1a808000
	v_lshlrev_b32_e32 v165, 4, v4
	v_lshlrev_b32_e32 v1, 6, v3
	v_and_b32_e32 v5, 32, v5
	s_addc_u32 s23, s3, 0
	v_bitop3_b32 v182, v165, v5, v1 bitop3:0x36
	v_mov_b32_e32 v1, v2
	v_mov_b32_e32 v167, v2
	s_cmp_lg_u64 s[38:39], 0
	v_lshlrev_b32_e32 v153, 3, v4
	v_mov_b32_e32 v147, v2
	v_mov_b32_e32 v169, v2
	v_cmp_eq_u32_e64 s[2:3], 0, v4
	s_cselect_b64 s[24:25], -1, 0
	v_lshl_add_u64 v[170:171], s[14:15], 0, v[0:1]
	v_lshl_add_u64 v[172:173], s[14:15], 0, v[166:167]
	s_mov_b64 s[4:5], -1
	s_mov_b64 s[26:27], 0
	s_branch .LBB0_452

; #define PG8_STAGE(bufoff, gbase, voff) do { _Pragma("unroll") for (int _i = 0; _i < 2; ++_i) \
;         __builtin_amdgcn_global_load_lds((const unsigned*)((const char*)(gbase) + (voff)[_i]), (PG8_LAS unsigned*)(lds + (bufoff) + ldsw + _i * 8192), 16, 0, 0); } while (0)
; #define PG8_WAIT_V(n) asm volatile("s_waitcnt vmcnt(" #n ")" ::: "memory")
; #define PG8_BAR __builtin_amdgcn_s_barrier()
; template <class Epi, class Sched, bool ALIGN_EPI = false, bool SP2 = false>
; __device__ __forceinline__ void gemm_phase(PG8_LAS unsigned char* lds, const Gemm g, const Sched& S, const Epi& E, const int tid) {
;     ...
;     if constexpr (SP2) {
;         PG8_STAGE(PG8_SB(0, 0), cB, voffB); PG8_STAGE(PG8_SB(0, 1), cB + hstep, voffB); PG8_STAGE(PG8_SA(0, 0), cA, voffA); PG8_STAGE(PG8_SA(0, 1), cA + hstep, voffA);
;         if (wr == 1) PG8_BAR;
;         PG8_WAIT_V(2); PG8_BAR;
;         PG8_STAGE(PG8_SB(1, 0), cB + kstep, voffB); PG8_STAGE(PG8_SA(1, 0), cA + kstep, voffA); PG8_STAGE(PG8_SB(1, 1), cB + hstep + kstep, voffB);
;         PG8_WAIT_V(6); PG8_BAR;
.LBB0_464:
	s_add_i32 m0, s62, 0x18000
	v_lshl_add_u64 v[8:9], v[8:9], 0, s[0:1]
	s_waitcnt vmcnt(2)
	s_barrier
	global_load_lds_dwordx4 v[8:9], off
	v_lshl_add_u64 v[8:9], v[10:11], 0, s[0:1]
	s_add_i32 m0, s62, 0x1a000
	s_add_i32 s66, s62, 0x8000
	global_load_lds_dwordx4 v[8:9], off
	v_lshl_add_u64 v[8:9], v[14:15], 0, s[0:1]
	s_mov_b32 m0, s66
	s_add_i32 s67, s62, 0xa000
	global_load_lds_dwordx4 v[8:9], off
	v_lshl_add_u64 v[8:9], v[12:13], 0, s[0:1]
	s_mov_b32 m0, s67
	v_lshl_add_u64 v[4:5], v[4:5], 0, s[0:1]
	global_load_lds_dwordx4 v[8:9], off
	s_add_i32 m0, s62, 0x1c000
	s_lshr_b32 s69, s37, 6
	global_load_lds_dwordx4 v[4:5], off
	v_lshl_add_u64 v[4:5], v[6:7], 0, s[0:1]
	s_add_i32 m0, s62, 0x1e000
	s_and_b32 s68, s5, 3
	global_load_lds_dwordx4 v[4:5], off
	v_lshl_or_b32 v183, s4, 6, v3
	s_lshl_b32 s4, s4, 13
	s_add_i32 s70, s69, -2
	s_cmpk_lt_u32 s50, 0x100
	v_lshlrev_b32_e32 v5, 2, v3
	s_cselect_b64 s[50:51], -1, 0
	s_lshr_b32 s71, s36, 3
	v_lshl_or_b32 v4, v3, 6, v165
	v_and_b32_e32 v5, 32, v5
	global_load_dword v250, v255, s[6:7] offset:256
	s_waitcnt vmcnt(7)
	s_and_b32 s72, s36, 7
	s_add_i32 s73, s71, 1
	v_bitop3_b32 v4, v4, s4, v5 bitop3:0xde
	s_cmp_lg_u64 s[40:41], 0
	v_lshl_or_b32 v184, s68, 12, v182
	v_lshl_or_b32 v185, s68, 5, v153
	s_mov_b32 s37, s35
	s_mov_b32 s74, 0
	s_cselect_b64 s[52:53], -1, 0
	v_add_u32_e32 v186, 0, v4
	s_barrier
	s_branch .LBB0_467

; #define PG8_STAGE(bufoff, gbase, voff) do { _Pragma("unroll") for (int _i = 0; _i < 2; ++_i) \
;         __builtin_amdgcn_global_load_lds((const unsigned*)((const char*)(gbase) + (voff)[_i]), (PG8_LAS unsigned*)(lds + (bufoff) + ldsw + _i * 8192), 16, 0, 0); } while (0)
; #define PG8_LDA(dst, b, h) do { _Pragma("unroll") for (int m = 0; m < 4; ++m) _Pragma("unroll") for (int k = 0; k < 2; ++k) dst[m][k] = *(const PG8_LAS bf16x8*)(lds + PG8_SA(b, h) + aoff + m * 2048 + k * 1024); } while (0)
; #define PG8_LDB(dst, b, h) do { _Pragma("unroll") for (int n = 0; n < 2; ++n) _Pragma("unroll") for (int k = 0; k < 2; ++k) dst[n][k] = *(const PG8_LAS bf16x8*)(lds + PG8_SB(b, h) + boff + n * 2048 + k * 1024); } while (0)
; #define PG8_MMA(ai, bj, At, Bt) do { __builtin_amdgcn_s_setprio(1); _Pragma("unroll") for (int m = 0; m < 4; ++m) _Pragma("unroll") for (int n = 0; n < 2; ++n) _Pragma("unroll") for (int k = 0; k < 2; ++k) \
;         acc[ai][bj][m][n] = __builtin_amdgcn_mfma_f32_16x16x32_bf16(Bt[n][k], At[m][k], acc[ai][bj][m][n], 0, 0, 0); __builtin_amdgcn_s_setprio(0); } while (0)
; #define PG8_WAIT_V(n) asm volatile("s_waitcnt vmcnt(" #n ")" ::: "memory")
; #define PG8_WAIT_L(n) asm volatile("s_waitcnt lgkmcnt(" #n ")" ::: "memory")
; #define PG8_BAR __builtin_amdgcn_s_barrier()
; #define PG8_SCHED __builtin_amdgcn_sched_barrier(0)
; template <class Epi, class Sched, bool ALIGN_EPI = false, bool SP2 = false>
; __device__ __forceinline__ void gemm_phase(PG8_LAS unsigned char* lds, const Gemm g, const Sched& S, const Epi& E, const int tid) {
;     ...
;             if constexpr (SP2) {
;             PG8_LDB(B0, 0, 0); PG8_LDB(B1, 0, 1); PG8_SCHED; PG8_LDA(At, 0, 0); PG8_STAGE(PG8_SA(1, 1), a1 + hstep, voffA);
;             PG8_WAIT_V(8); PG8_WAIT_L(0); PG8_BAR; PG8_MMA(0, 0, At, B0); PG8_MMA(0, 1, At, B1); PG8_BAR; PG8_SCHED;
;             PG8_LDA(At, 0, 1); PG8_STAGE(PG8_SB(0, 0), b2, voffB); PG8_STAGE(PG8_SB(0, 1), b2 + hstep, voffB); PG8_STAGE(PG8_SA(0, 0), a2, voffA);
;             PG8_WAIT_V(8); PG8_WAIT_L(0); PG8_BAR; PG8_MMA(1, 0, At, B0); PG8_MMA(1, 1, At, B1); PG8_BAR; PG8_SCHED;
.LBB0_476:
	s_add_i32 s80, s58, 2
	s_add_u32 s81, s6, 0x80
	s_addc_u32 s59, s7, 0
	s_add_i32 s87, 0, 0x10000
	s_cmp_eq_u32 s70, s58
	s_cselect_b32 s59, s55, s59
	s_cselect_b32 s58, s54, s81
	v_add_u32_e32 v144, s87, v184
	s_cselect_b32 s83, s57, s79
	s_cselect_b32 s82, s56, s78
	s_add_i32 s81, 0, 0x14000
	ds_read_b128 v[132:135], v144
	ds_read_b128 v[136:139], v144 offset:1024
	ds_read_b128 v[140:143], v144 offset:2048
	ds_read_b128 v[174:177], v144 offset:3072
	v_add_u32_e32 v144, s81, v184
	ds_read_b128 v[178:181], v144
	ds_read_b128 v[188:191], v144 offset:1024
	ds_read_b128 v[192:195], v144 offset:2048
	ds_read_b128 v[196:199], v144 offset:3072
	v_lshl_add_u64 v[144:145], s[6:7], 0, v[170:171]
	s_add_i32 m0, s62, 0xc000
	ds_read_b128 v[200:203], v186
	ds_read_b128 v[204:207], v186 offset:1024
	ds_read_b128 v[208:211], v186 offset:2048
	ds_read_b128 v[212:215], v186 offset:3072
	ds_read_b128 v[216:219], v186 offset:4096
	ds_read_b128 v[220:223], v186 offset:5120
	ds_read_b128 v[224:227], v186 offset:6144
	ds_read_b128 v[238:241], v186 offset:7168
	global_load_lds_dwordx4 v[144:145], off
	v_lshl_add_u64 v[144:145], s[6:7], 0, v[172:173]
	s_add_i32 m0, s62, 0xe000
	s_nop 0
	global_load_lds_dwordx4 v[144:145], off
	s_waitcnt vmcnt(9)
	s_waitcnt lgkmcnt(0)
	s_barrier
	s_setprio 1
	s_waitcnt lgkmcnt(0)
	v_mfma_f32_16x16x32_bf16 v[128:131], v[132:135], v[200:203], v[128:131]
	v_mfma_f32_16x16x32_bf16 v[124:127], v[140:143], v[200:203], v[124:127]
	v_mfma_f32_16x16x32_bf16 v[112:115], v[132:135], v[208:211], v[112:115]
	v_mfma_f32_16x16x32_bf16 v[108:111], v[140:143], v[208:211], v[108:111]
	v_mfma_f32_16x16x32_bf16 v[96:99], v[132:135], v[216:219], v[96:99]
	v_mfma_f32_16x16x32_bf16 v[92:95], v[140:143], v[216:219], v[92:95]
	v_mfma_f32_16x16x32_bf16 v[80:83], v[132:135], v[224:227], v[80:83]
	v_mfma_f32_16x16x32_bf16 v[76:79], v[140:143], v[224:227], v[76:79]
	v_mfma_f32_16x16x32_bf16 v[128:131], v[136:139], v[204:207], v[128:131]
	v_mfma_f32_16x16x32_bf16 v[124:127], v[174:177], v[204:207], v[124:127]
	v_mfma_f32_16x16x32_bf16 v[112:115], v[136:139], v[212:215], v[112:115]
	v_mfma_f32_16x16x32_bf16 v[108:111], v[174:177], v[212:215], v[108:111]
	v_mfma_f32_16x16x32_bf16 v[96:99], v[136:139], v[220:223], v[96:99]
	v_mfma_f32_16x16x32_bf16 v[92:95], v[174:177], v[220:223], v[92:95]
	v_mfma_f32_16x16x32_bf16 v[80:83], v[136:139], v[238:241], v[80:83]
	v_mfma_f32_16x16x32_bf16 v[76:79], v[174:177], v[238:241], v[76:79]
	s_setprio 0
	s_setprio 1
	v_mfma_f32_16x16x32_bf16 v[120:123], v[178:181], v[200:203], v[120:123]
	v_mfma_f32_16x16x32_bf16 v[116:119], v[192:195], v[200:203], v[116:119]
	v_mfma_f32_16x16x32_bf16 v[104:107], v[178:181], v[208:211], v[104:107]
	v_mfma_f32_16x16x32_bf16 v[100:103], v[192:195], v[208:211], v[100:103]
	v_mfma_f32_16x16x32_bf16 v[88:91], v[178:181], v[216:219], v[88:91]
	v_mfma_f32_16x16x32_bf16 v[84:87], v[192:195], v[216:219], v[84:87]
	v_mfma_f32_16x16x32_bf16 v[72:75], v[178:181], v[224:227], v[72:75]
	v_mfma_f32_16x16x32_bf16 v[68:71], v[192:195], v[224:227], v[68:71]
	v_mfma_f32_16x16x32_bf16 v[120:123], v[188:191], v[204:207], v[120:123]
	v_mfma_f32_16x16x32_bf16 v[116:119], v[196:199], v[204:207], v[116:119]
	v_mfma_f32_16x16x32_bf16 v[104:107], v[188:191], v[212:215], v[104:107]
	v_mfma_f32_16x16x32_bf16 v[100:103], v[196:199], v[212:215], v[100:103]
	v_mfma_f32_16x16x32_bf16 v[88:91], v[188:191], v[220:223], v[88:91]
	v_mfma_f32_16x16x32_bf16 v[84:87], v[196:199], v[220:223], v[84:87]
	v_mfma_f32_16x16x32_bf16 v[72:75], v[188:191], v[238:241], v[72:75]
	v_mfma_f32_16x16x32_bf16 v[68:71], v[196:199], v[238:241], v[68:71]
	s_setprio 0
	s_barrier
	s_add_i32 s87, s87, s61
	v_lshl_add_u64 v[144:145], s[82:83], 0, v[146:147]
	s_mov_b32 m0, s87
	ds_read_b128 v[200:203], v186 offset:16384
	ds_read_b128 v[204:207], v186 offset:17408
	ds_read_b128 v[208:211], v186 offset:18432
	ds_read_b128 v[212:215], v186 offset:19456
	ds_read_b128 v[216:219], v186 offset:20480
	ds_read_b128 v[220:223], v186 offset:21504
	ds_read_b128 v[224:227], v186 offset:22528
	ds_read_b128 v[238:241], v186 offset:23552
	global_load_lds_dwordx4 v[144:145], off
	s_add_i32 m0, s87, 0x2000
	v_lshl_add_u64 v[242:243], s[82:83], 0, v[168:169]
	s_add_u32 s82, s82, s14
	s_addc_u32 s83, s83, 0
	s_add_i32 s81, s81, s61
	global_load_lds_dwordx4 v[242:243], off
	v_lshl_add_u64 v[244:245], s[82:83], 0, v[146:147]
	s_mov_b32 m0, s81
	v_lshl_add_u64 v[246:247], s[82:83], 0, v[168:169]
	global_load_lds_dwordx4 v[244:245], off
	s_add_i32 m0, s81, 0x2000
	v_lshl_add_u64 v[248:249], s[58:59], 0, v[0:1]
	global_load_lds_dwordx4 v[246:247], off
	s_mov_b32 m0, s62
	v_lshl_add_u64 v[148:149], s[58:59], 0, v[166:167]
	global_load_lds_dwordx4 v[248:249], off
	s_mov_b32 m0, s63
	s_nop 0
	global_load_lds_dwordx4 v[148:149], off
	s_waitcnt vmcnt(9)
	s_waitcnt lgkmcnt(0)
	s_barrier
; #define PG8_STAGE(bufoff, gbase, voff) do { _Pragma("unroll") for (int _i = 0; _i < 2; ++_i) \
;         __builtin_amdgcn_global_load_lds((const unsigned*)((const char*)(gbase) + (voff)[_i]), (PG8_LAS unsigned*)(lds + (bufoff) + ldsw + _i * 8192), 16, 0, 0); } while (0)
; #define PG8_LDA(dst, b, h) do { _Pragma("unroll") for (int m = 0; m < 4; ++m) _Pragma("unroll") for (int k = 0; k < 2; ++k) dst[m][k] = *(const PG8_LAS bf16x8*)(lds + PG8_SA(b, h) + aoff + m * 2048 + k * 1024); } while (0)
; #define PG8_LDB(dst, b, h) do { _Pragma("unroll") for (int n = 0; n < 2; ++n) _Pragma("unroll") for (int k = 0; k < 2; ++k) dst[n][k] = *(const PG8_LAS bf16x8*)(lds + PG8_SB(b, h) + boff + n * 2048 + k * 1024); } while (0)
; #define PG8_MMA(ai, bj, At, Bt) do { __builtin_amdgcn_s_setprio(1); _Pragma("unroll") for (int m = 0; m < 4; ++m) _Pragma("unroll") for (int n = 0; n < 2; ++n) _Pragma("unroll") for (int k = 0; k < 2; ++k) \
;         acc[ai][bj][m][n] = __builtin_amdgcn_mfma_f32_16x16x32_bf16(Bt[n][k], At[m][k], acc[ai][bj][m][n], 0, 0, 0); __builtin_amdgcn_s_setprio(0); } while (0)
; #define PG8_WAIT_V(n) asm volatile("s_waitcnt vmcnt(" #n ")" ::: "memory")
; #define PG8_WAIT_L(n) asm volatile("s_waitcnt lgkmcnt(" #n ")" ::: "memory")
; #define PG8_BAR __builtin_amdgcn_s_barrier()
; #define PG8_SCHED __builtin_amdgcn_sched_barrier(0)
; template <class Epi, class Sched, bool ALIGN_EPI = false, bool SP2 = false>
; __device__ __forceinline__ void gemm_phase(PG8_LAS unsigned char* lds, const Gemm g, const Sched& S, const Epi& E, const int tid) {
;     ...
;             PG8_WAIT_V(8); PG8_WAIT_L(0); PG8_BAR; PG8_MMA(1, 0, At, B0); PG8_MMA(1, 1, At, B1); PG8_BAR; PG8_SCHED;
;             PG8_LDB(B0, 1, 0); PG8_LDB(B1, 1, 1); PG8_SCHED; PG8_LDA(At, 1, 0); PG8_STAGE(PG8_SA(0, 1), a2 + hstep, voffA);
;             PG8_WAIT_V(8); PG8_WAIT_L(0); PG8_BAR; PG8_MMA(0, 0, At, B0); PG8_MMA(0, 1, At, B1); PG8_BAR; PG8_SCHED;
	s_setprio 1
	s_waitcnt lgkmcnt(0)
	v_mfma_f32_16x16x32_bf16 v[64:67], v[132:135], v[200:203], v[64:67]
	v_mfma_f32_16x16x32_bf16 v[60:63], v[140:143], v[200:203], v[60:63]
	v_mfma_f32_16x16x32_bf16 v[48:51], v[132:135], v[208:211], v[48:51]
	v_mfma_f32_16x16x32_bf16 v[44:47], v[140:143], v[208:211], v[44:47]
	v_mfma_f32_16x16x32_bf16 v[32:35], v[132:135], v[216:219], v[32:35]
	v_mfma_f32_16x16x32_bf16 v[28:31], v[140:143], v[216:219], v[28:31]
	v_mfma_f32_16x16x32_bf16 v[16:19], v[132:135], v[224:227], v[16:19]
	v_mfma_f32_16x16x32_bf16 v[12:15], v[140:143], v[224:227], v[12:15]
	v_mfma_f32_16x16x32_bf16 v[64:67], v[136:139], v[204:207], v[64:67]
	v_mfma_f32_16x16x32_bf16 v[60:63], v[174:177], v[204:207], v[60:63]
	v_mfma_f32_16x16x32_bf16 v[48:51], v[136:139], v[212:215], v[48:51]
	v_mfma_f32_16x16x32_bf16 v[44:47], v[174:177], v[212:215], v[44:47]
	v_mfma_f32_16x16x32_bf16 v[32:35], v[136:139], v[220:223], v[32:35]
	v_mfma_f32_16x16x32_bf16 v[28:31], v[174:177], v[220:223], v[28:31]
	v_mfma_f32_16x16x32_bf16 v[16:19], v[136:139], v[238:241], v[16:19]
	v_mfma_f32_16x16x32_bf16 v[12:15], v[174:177], v[238:241], v[12:15]
	s_setprio 0
	s_setprio 1
	v_mfma_f32_16x16x32_bf16 v[56:59], v[178:181], v[200:203], v[56:59]
	v_mfma_f32_16x16x32_bf16 v[52:55], v[192:195], v[200:203], v[52:55]
	v_mfma_f32_16x16x32_bf16 v[40:43], v[178:181], v[208:211], v[40:43]
	v_mfma_f32_16x16x32_bf16 v[36:39], v[192:195], v[208:211], v[36:39]
	v_mfma_f32_16x16x32_bf16 v[24:27], v[178:181], v[216:219], v[24:27]
	v_mfma_f32_16x16x32_bf16 v[20:23], v[192:195], v[216:219], v[20:23]
	v_mfma_f32_16x16x32_bf16 v[8:11], v[178:181], v[224:227], v[8:11]
	v_mfma_f32_16x16x32_bf16 v[4:7], v[192:195], v[224:227], v[4:7]
	v_mfma_f32_16x16x32_bf16 v[56:59], v[188:191], v[204:207], v[56:59]
	v_mfma_f32_16x16x32_bf16 v[52:55], v[196:199], v[204:207], v[52:55]
	v_mfma_f32_16x16x32_bf16 v[40:43], v[188:191], v[212:215], v[40:43]
	v_mfma_f32_16x16x32_bf16 v[36:39], v[196:199], v[212:215], v[36:39]
	v_mfma_f32_16x16x32_bf16 v[24:27], v[188:191], v[220:223], v[24:27]
	v_mfma_f32_16x16x32_bf16 v[20:23], v[196:199], v[220:223], v[20:23]
	v_mfma_f32_16x16x32_bf16 v[8:11], v[188:191], v[238:241], v[8:11]
	v_mfma_f32_16x16x32_bf16 v[4:7], v[196:199], v[238:241], v[4:7]
	s_setprio 0
	s_barrier
	s_add_i32 s81, 0, 0x18000
	v_add_u32_e32 v150, s81, v184
	s_add_i32 s82, 0, 0x1c000
	ds_read_b128 v[132:135], v150
	ds_read_b128 v[136:139], v150 offset:1024
	ds_read_b128 v[140:143], v150 offset:2048
	ds_read_b128 v[174:177], v150 offset:3072
	v_add_u32_e32 v150, s82, v184
	ds_read_b128 v[178:181], v150
	ds_read_b128 v[188:191], v150 offset:1024
	ds_read_b128 v[192:195], v150 offset:2048
	ds_read_b128 v[196:199], v150 offset:3072
	s_add_u32 s58, s58, s14
	s_addc_u32 s59, s59, 0
	s_mov_b32 m0, s64
	v_lshl_add_u64 v[150:151], s[58:59], 0, v[0:1]
	ds_read_b128 v[200:203], v186 offset:32768
	ds_read_b128 v[204:207], v186 offset:33792
	ds_read_b128 v[208:211], v186 offset:34816
	ds_read_b128 v[212:215], v186 offset:35840
	ds_read_b128 v[216:219], v186 offset:36864
	ds_read_b128 v[220:223], v186 offset:37888
	ds_read_b128 v[224:227], v186 offset:38912
	ds_read_b128 v[238:241], v186 offset:39936
	global_load_lds_dwordx4 v[150:151], off
	v_lshl_add_u64 v[150:151], s[58:59], 0, v[166:167]
	s_mov_b32 m0, s65
	s_nop 0
	global_load_lds_dwordx4 v[150:151], off
	s_waitcnt vmcnt(8)
	s_waitcnt lgkmcnt(0)
	s_barrier
	s_setprio 1
	s_waitcnt lgkmcnt(0)
	v_mfma_f32_16x16x32_bf16 v[128:131], v[132:135], v[200:203], v[128:131]
	v_mfma_f32_16x16x32_bf16 v[124:127], v[140:143], v[200:203], v[124:127]
	v_mfma_f32_16x16x32_bf16 v[112:115], v[132:135], v[208:211], v[112:115]
	v_mfma_f32_16x16x32_bf16 v[108:111], v[140:143], v[208:211], v[108:111]
	v_mfma_f32_16x16x32_bf16 v[96:99], v[132:135], v[216:219], v[96:99]
	v_mfma_f32_16x16x32_bf16 v[92:95], v[140:143], v[216:219], v[92:95]
	v_mfma_f32_16x16x32_bf16 v[80:83], v[132:135], v[224:227], v[80:83]
	v_mfma_f32_16x16x32_bf16 v[76:79], v[140:143], v[224:227], v[76:79]
	v_mfma_f32_16x16x32_bf16 v[128:131], v[136:139], v[204:207], v[128:131]
	v_mfma_f32_16x16x32_bf16 v[124:127], v[174:177], v[204:207], v[124:127]
	v_mfma_f32_16x16x32_bf16 v[112:115], v[136:139], v[212:215], v[112:115]
	v_mfma_f32_16x16x32_bf16 v[108:111], v[174:177], v[212:215], v[108:111]
	v_mfma_f32_16x16x32_bf16 v[96:99], v[136:139], v[220:223], v[96:99]
	v_mfma_f32_16x16x32_bf16 v[92:95], v[174:177], v[220:223], v[92:95]
	v_mfma_f32_16x16x32_bf16 v[80:83], v[136:139], v[238:241], v[80:83]
	v_mfma_f32_16x16x32_bf16 v[76:79], v[174:177], v[238:241], v[76:79]
	s_setprio 0
	s_setprio 1
	v_mfma_f32_16x16x32_bf16 v[120:123], v[178:181], v[200:203], v[120:123]
	v_mfma_f32_16x16x32_bf16 v[116:119], v[192:195], v[200:203], v[116:119]
	v_mfma_f32_16x16x32_bf16 v[104:107], v[178:181], v[208:211], v[104:107]
	v_mfma_f32_16x16x32_bf16 v[100:103], v[192:195], v[208:211], v[100:103]
	v_mfma_f32_16x16x32_bf16 v[88:91], v[178:181], v[216:219], v[88:91]
	v_mfma_f32_16x16x32_bf16 v[84:87], v[192:195], v[216:219], v[84:87]
	v_mfma_f32_16x16x32_bf16 v[72:75], v[178:181], v[224:227], v[72:75]
	v_mfma_f32_16x16x32_bf16 v[68:71], v[192:195], v[224:227], v[68:71]
	v_mfma_f32_16x16x32_bf16 v[120:123], v[188:191], v[204:207], v[120:123]
	v_mfma_f32_16x16x32_bf16 v[116:119], v[196:199], v[204:207], v[116:119]
	v_mfma_f32_16x16x32_bf16 v[104:107], v[188:191], v[212:215], v[104:107]
	v_mfma_f32_16x16x32_bf16 v[100:103], v[196:199], v[212:215], v[100:103]
	v_mfma_f32_16x16x32_bf16 v[88:91], v[188:191], v[220:223], v[88:91]
	v_mfma_f32_16x16x32_bf16 v[84:87], v[196:199], v[220:223], v[84:87]
	v_mfma_f32_16x16x32_bf16 v[72:75], v[188:191], v[238:241], v[72:75]
	v_mfma_f32_16x16x32_bf16 v[68:71], v[196:199], v[238:241], v[68:71]
	s_setprio 0
	s_barrier
; #define PG8_STAGE(bufoff, gbase, voff) do { _Pragma("unroll") for (int _i = 0; _i < 2; ++_i) \
;         __builtin_amdgcn_global_load_lds((const unsigned*)((const char*)(gbase) + (voff)[_i]), (PG8_LAS unsigned*)(lds + (bufoff) + ldsw + _i * 8192), 16, 0, 0); } while (0)
; #define PG8_LDA(dst, b, h) do { _Pragma("unroll") for (int m = 0; m < 4; ++m) _Pragma("unroll") for (int k = 0; k < 2; ++k) dst[m][k] = *(const PG8_LAS bf16x8*)(lds + PG8_SA(b, h) + aoff + m * 2048 + k * 1024); } while (0)
; #define PG8_MMA(ai, bj, At, Bt) do { __builtin_amdgcn_s_setprio(1); _Pragma("unroll") for (int m = 0; m < 4; ++m) _Pragma("unroll") for (int n = 0; n < 2; ++n) _Pragma("unroll") for (int k = 0; k < 2; ++k) \
;         acc[ai][bj][m][n] = __builtin_amdgcn_mfma_f32_16x16x32_bf16(Bt[n][k], At[m][k], acc[ai][bj][m][n], 0, 0, 0); __builtin_amdgcn_s_setprio(0); } while (0)
; #define PG8_WAIT_V(n) asm volatile("s_waitcnt vmcnt(" #n ")" ::: "memory")
; #define PG8_WAIT_L(n) asm volatile("s_waitcnt lgkmcnt(" #n ")" ::: "memory")
; #define PG8_BAR __builtin_amdgcn_s_barrier()
; #define PG8_SCHED __builtin_amdgcn_sched_barrier(0)
; template <class Epi, class Sched, bool ALIGN_EPI = false, bool SP2 = false>
; __device__ __forceinline__ void gemm_phase(PG8_LAS unsigned char* lds, const Gemm g, const Sched& S, const Epi& E, const int tid) {
;     ...
;         for (int t = 0; t < nt; t += 2) {
;             const bool last = (t == nt - 2);
;             const char* a1 = cA + (size_t)(t + 1) * kstep;
;             const char* a2 = last ? nA : cA + (size_t)(t + 2) * kstep; const char* b2 = last ? nB : cB + (size_t)(t + 2) * kstep;
;             const char* a3 = a2 + kstep; const char* b3 = b2 + kstep;
;     ...
;             PG8_LDA(At, 1, 1); PG8_STAGE(PG8_SB(1, 0), b3, voffB); PG8_STAGE(PG8_SB(1, 1), b3 + hstep, voffB); PG8_STAGE(PG8_SA(1, 0), a3, voffA);
;             PG8_WAIT_V(8); PG8_WAIT_L(0); PG8_BAR; PG8_MMA(1, 0, At, B0); PG8_MMA(1, 1, At, B1); PG8_BAR; PG8_SCHED;
	s_add_i32 s58, s81, s61
	v_lshl_add_u64 v[144:145], v[144:145], 0, s[0:1]
	s_mov_b32 m0, s58
	ds_read_b128 v[200:203], v186 offset:49152
	ds_read_b128 v[204:207], v186 offset:50176
	ds_read_b128 v[208:211], v186 offset:51200
	ds_read_b128 v[212:215], v186 offset:52224
	ds_read_b128 v[216:219], v186 offset:53248
	ds_read_b128 v[220:223], v186 offset:54272
	ds_read_b128 v[224:227], v186 offset:55296
	ds_read_b128 v[238:241], v186 offset:56320
	global_load_lds_dwordx4 v[144:145], off
	v_lshl_add_u64 v[144:145], v[242:243], 0, s[0:1]
	s_add_i32 m0, s58, 0x2000
	s_add_i32 s58, s82, s61
	global_load_lds_dwordx4 v[144:145], off
	v_lshl_add_u64 v[144:145], v[244:245], 0, s[0:1]
	s_mov_b32 m0, s58
	s_nop 0
	global_load_lds_dwordx4 v[144:145], off
	v_lshl_add_u64 v[144:145], v[246:247], 0, s[0:1]
	s_add_i32 m0, s58, 0x2000
	s_nop 0
	global_load_lds_dwordx4 v[144:145], off
	v_lshl_add_u64 v[144:145], v[248:249], 0, s[0:1]
	s_mov_b32 m0, s66
	s_nop 0
	global_load_lds_dwordx4 v[144:145], off
	v_lshl_add_u64 v[144:145], v[148:149], 0, s[0:1]
	s_mov_b32 m0, s67
	s_nop 0
	global_load_lds_dwordx4 v[144:145], off
	global_load_dword v250, v255, s[6:7] offset:384
	s_waitcnt vmcnt(9)
	s_waitcnt lgkmcnt(0)
	s_barrier
	s_setprio 1
	s_waitcnt lgkmcnt(0)
	v_mfma_f32_16x16x32_bf16 v[64:67], v[132:135], v[200:203], v[64:67]
	v_mfma_f32_16x16x32_bf16 v[60:63], v[140:143], v[200:203], v[60:63]
	v_mfma_f32_16x16x32_bf16 v[48:51], v[132:135], v[208:211], v[48:51]
	v_mfma_f32_16x16x32_bf16 v[44:47], v[140:143], v[208:211], v[44:47]
	v_mfma_f32_16x16x32_bf16 v[32:35], v[132:135], v[216:219], v[32:35]
	v_mfma_f32_16x16x32_bf16 v[28:31], v[140:143], v[216:219], v[28:31]
	v_mfma_f32_16x16x32_bf16 v[16:19], v[132:135], v[224:227], v[16:19]
	v_mfma_f32_16x16x32_bf16 v[12:15], v[140:143], v[224:227], v[12:15]
	v_mfma_f32_16x16x32_bf16 v[64:67], v[136:139], v[204:207], v[64:67]
	v_mfma_f32_16x16x32_bf16 v[60:63], v[174:177], v[204:207], v[60:63]
	v_mfma_f32_16x16x32_bf16 v[48:51], v[136:139], v[212:215], v[48:51]
	v_mfma_f32_16x16x32_bf16 v[44:47], v[174:177], v[212:215], v[44:47]
	v_mfma_f32_16x16x32_bf16 v[32:35], v[136:139], v[220:223], v[32:35]
	v_mfma_f32_16x16x32_bf16 v[28:31], v[174:177], v[220:223], v[28:31]
	v_mfma_f32_16x16x32_bf16 v[16:19], v[136:139], v[238:241], v[16:19]
	v_mfma_f32_16x16x32_bf16 v[12:15], v[174:177], v[238:241], v[12:15]
	s_setprio 0
	s_setprio 1
	v_mfma_f32_16x16x32_bf16 v[56:59], v[178:181], v[200:203], v[56:59]
	v_mfma_f32_16x16x32_bf16 v[52:55], v[192:195], v[200:203], v[52:55]
	v_mfma_f32_16x16x32_bf16 v[40:43], v[178:181], v[208:211], v[40:43]
	v_mfma_f32_16x16x32_bf16 v[36:39], v[192:195], v[208:211], v[36:39]
	v_mfma_f32_16x16x32_bf16 v[24:27], v[178:181], v[216:219], v[24:27]
	v_mfma_f32_16x16x32_bf16 v[20:23], v[192:195], v[216:219], v[20:23]
	v_mfma_f32_16x16x32_bf16 v[8:11], v[178:181], v[224:227], v[8:11]
	v_mfma_f32_16x16x32_bf16 v[4:7], v[192:195], v[224:227], v[4:7]
	v_mfma_f32_16x16x32_bf16 v[56:59], v[188:191], v[204:207], v[56:59]
	v_mfma_f32_16x16x32_bf16 v[52:55], v[196:199], v[204:207], v[52:55]
	v_mfma_f32_16x16x32_bf16 v[40:43], v[188:191], v[212:215], v[40:43]
	v_mfma_f32_16x16x32_bf16 v[36:39], v[196:199], v[212:215], v[36:39]
	v_mfma_f32_16x16x32_bf16 v[24:27], v[188:191], v[220:223], v[24:27]
	v_mfma_f32_16x16x32_bf16 v[20:23], v[196:199], v[220:223], v[20:23]
	v_mfma_f32_16x16x32_bf16 v[8:11], v[188:191], v[238:241], v[8:11]
	v_mfma_f32_16x16x32_bf16 v[4:7], v[196:199], v[238:241], v[4:7]
	s_setprio 0
	s_barrier
	s_add_u32 s6, s6, 0x100
	s_addc_u32 s7, s7, 0
	s_add_u32 s78, s78, 0x100
	s_addc_u32 s79, s79, 0
	s_cmp_ge_u32 s80, s69
	s_mov_b32 s58, s80
	s_cbranch_scc0 .LBB0_476
	s_and_b64 vcc, exec, s[50:51]
	s_cbranch_vccz .LBB0_479
	s_barrier

; __global__ void __launch_bounds__(512, 2) hybrid_fwd(Args args) {
	.amdhsa_kernel _Z10hybrid_fwd4Args
		.amdhsa_group_segment_fixed_size 0
		.amdhsa_private_segment_fixed_size 0
		.amdhsa_kernarg_size 496
		.amdhsa_user_sgpr_count 2
		.amdhsa_user_sgpr_dispatch_ptr 0
		.amdhsa_user_sgpr_queue_ptr 0
		.amdhsa_user_sgpr_kernarg_segment_ptr 1
		.amdhsa_user_sgpr_dispatch_id 0
		.amdhsa_user_sgpr_kernarg_preload_length 0
		.amdhsa_user_sgpr_kernarg_preload_offset 0
		.amdhsa_user_sgpr_private_segment_size 0
		.amdhsa_uses_dynamic_stack 0
		.amdhsa_enable_private_segment 0
		.amdhsa_system_sgpr_workgroup_id_x 1
		.amdhsa_system_sgpr_workgroup_id_y 0
		.amdhsa_system_sgpr_workgroup_id_z 0
		.amdhsa_system_sgpr_workgroup_info 0
		.amdhsa_system_vgpr_workitem_id 2
		.amdhsa_next_free_vgpr 256
		.amdhsa_next_free_sgpr 100
		.amdhsa_accum_offset 256
		.amdhsa_reserve_vcc 1
		.amdhsa_float_round_mode_32 0
		.amdhsa_float_round_mode_16_64 0
		.amdhsa_float_denorm_mode_32 3
		.amdhsa_float_denorm_mode_16_64 3
		.amdhsa_dx10_clamp 1
		.amdhsa_ieee_mode 1
		.amdhsa_fp16_overflow 0
		.amdhsa_tg_split 0
		.amdhsa_exception_fp_ieee_invalid_op 0
		.amdhsa_exception_fp_denorm_src 0
		.amdhsa_exception_fp_ieee_div_zero 0
		.amdhsa_exception_fp_ieee_overflow 0
		.amdhsa_exception_fp_ieee_underflow 0
		.amdhsa_exception_fp_ieee_inexact 0
		.amdhsa_exception_int_div_zero 0
	.end_amdhsa_kernel

; __global__ void __launch_bounds__(512, 2) hybrid_fwd(Args args) {
amdhsa.kernels:
  - .agpr_count:     0
    .args:
      - .offset:         0
        .size:           240
        .value_kind:     by_value
      - .offset:         240
        .size:           4
        .value_kind:     hidden_block_count_x
      - .offset:         244
        .size:           4
        .value_kind:     hidden_block_count_y
      - .offset:         248
        .size:           4
        .value_kind:     hidden_block_count_z
      - .offset:         252
        .size:           2
        .value_kind:     hidden_group_size_x
      - .offset:         254
        .size:           2
        .value_kind:     hidden_group_size_y
      - .offset:         256
        .size:           2
        .value_kind:     hidden_group_size_z
      - .offset:         258
        .size:           2
        .value_kind:     hidden_remainder_x
      - .offset:         260
        .size:           2
        .value_kind:     hidden_remainder_y
      - .offset:         262
        .size:           2
        .value_kind:     hidden_remainder_z
      - .offset:         280
        .size:           8
        .value_kind:     hidden_global_offset_x
      - .offset:         288
        .size:           8
        .value_kind:     hidden_global_offset_y
      - .offset:         296
        .size:           8
        .value_kind:     hidden_global_offset_z
      - .offset:         304
        .size:           2
        .value_kind:     hidden_grid_dims
      - .offset:         328
        .size:           8
        .value_kind:     hidden_multigrid_sync_arg
      - .offset:         360
        .size:           4
        .value_kind:     hidden_dynamic_lds_size
    .group_segment_fixed_size: 0
    .kernarg_segment_align: 8
    .kernarg_segment_size: 496
    .language:       OpenCL C
    .language_version:
      - 2
      - 0
    .max_flat_workgroup_size: 512
    .name:           _Z10hybrid_fwd4Args
    .private_segment_fixed_size: 0
    .sgpr_count:     106
    .sgpr_spill_count: 297
    .symbol:         _Z10hybrid_fwd4Args.kd
    .uniform_work_group_size: 1
    .uses_dynamic_stack: false
    .vgpr_count:     256
    .vgpr_spill_count: 0
    .wavefront_size: 64
